# v30 plus attention: first-half V-fragment ds_reads hoisted above the softmax VALU (LDS latency hidden under exp/cvt), into dead VGPRs
# baseline (speedup 1.0000x reference)
; #define LAS __attribute__((address_space(3)))
; DI f32x4 mfma16(bf16x8 a, bf16x8 b, f32x4 c) { return __builtin_amdgcn_mfma_f32_16x16x32_bf16(a, b, c, 0, 0, 0); }
; DI float fast_exp2(float x) { return __builtin_amdgcn_exp2f(x); }
; #define SCHED __builtin_amdgcn_sched_barrier(0)
; DI void attn_item(const Params& p, int layer, int b, int hh, int jq, lchar* sm, float lam, float oml, int tid, int w) {
;     ...
;         for (int k16 = 0; k16 < 4; ++k16)
; #pragma unroll
;           for (int r = 0; r < 4; ++r) S[m][k16][r] = fast_exp2(S[m][k16][r]);
; #pragma unroll
;         for (int kk = 0; kk < 2; ++kk) {
;           u32x4 t;
;           t[0] = pack2(S[m][2 * kk][0], S[m][2 * kk][1]); t[1] = pack2(S[m][2 * kk][2], S[m][2 * kk][3]);
;           t[2] = pack2(S[m][2 * kk + 1][0], S[m][2 * kk + 1][1]); t[3] = pack2(S[m][2 * kk + 1][2], S[m][2 * kk + 1][3]);
;           pb[m][kk] = __builtin_bit_cast(bf16x8, t);
;           Osum[m] = mfma16(ones, pb[m][kk], Osum[m]);
;         }
;       }
; #pragma unroll
;       for (int kk = 0; kk < 2; ++kk) {
;         bf16x8 vf[8];
; #pragma unroll
;         for (int dt = 0; dt < 8; ++dt) vf[dt] = *(const LAS bf16x8*)(vb + dt * 2048 + voff[kk]);
;         SCHED;
; #pragma unroll
;         for (int dt = 0; dt < 8; ++dt) {
;           O[0][dt] = mfma16(vf[dt], pb[0][kk], O[0][dt]);
;           O[1][dt] = mfma16(vf[dt], pb[1][kk], O[1][dt]);
;         }
;       }
.LBB0_167:
	v_exp_f32_e32 v96, v96
	v_exp_f32_e32 v97, v97
	v_exp_f32_e32 v98, v98
	v_exp_f32_e32 v99, v99
	v_exp_f32_e32 v116, v92
	v_exp_f32_e32 v117, v93
	v_exp_f32_e32 v118, v94
	v_exp_f32_e32 v95, v95
	v_exp_f32_e32 v100, v100
	v_exp_f32_e32 v101, v101
	v_exp_f32_e32 v102, v102
	v_exp_f32_e32 v103, v103
	v_exp_f32_e32 v104, v104
	v_exp_f32_e32 v105, v105
	v_exp_f32_e32 v106, v106
	v_exp_f32_e32 v107, v107
	v_cvt_pk_bf16_f32 v92, v96, v97
	v_cvt_pk_bf16_f32 v93, v98, v99
	v_cvt_pk_bf16_f32 v94, v116, v117
	v_cvt_pk_bf16_f32 v95, v118, v95
	v_cvt_pk_bf16_f32 v96, v100, v101
	v_cvt_pk_bf16_f32 v97, v102, v103
	v_cvt_pk_bf16_f32 v98, v104, v105
	v_cvt_pk_bf16_f32 v99, v106, v107
	v_add_u32_e32 v165, s73, v154
	v_mfma_f32_16x16x32_bf16 v[88:91], v[0:3], v[92:95], v[88:91]
	v_mfma_f32_16x16x32_bf16 v[88:91], v[0:3], v[96:99], v[88:91]
	s_waitcnt lgkmcnt(0)
	v_mfma_f32_16x16x32_bf16 v[80:83], v[206:209], v[112:115], v[80:83]
	v_mfma_f32_16x16x32_bf16 v[84:87], v[206:209], v[92:95], v[84:87]
	v_mfma_f32_16x16x32_bf16 v[72:75], v[210:213], v[112:115], v[72:75]
	v_mfma_f32_16x16x32_bf16 v[76:79], v[210:213], v[92:95], v[76:79]
	v_mfma_f32_16x16x32_bf16 v[64:67], v[214:217], v[112:115], v[64:67]
	v_mfma_f32_16x16x32_bf16 v[68:71], v[214:217], v[92:95], v[68:71]
	v_mfma_f32_16x16x32_bf16 v[56:59], v[218:221], v[112:115], v[56:59]
	v_mfma_f32_16x16x32_bf16 v[60:63], v[218:221], v[92:95], v[60:63]
	ds_read_b128 v[100:103], v165 offset:16384
	ds_read_b128 v[104:107], v165 offset:18432
	ds_read_b128 v[116:119], v165 offset:20480
	ds_read_b128 v[120:123], v165 offset:22528
	v_mfma_f32_16x16x32_bf16 v[48:51], v[222:225], v[112:115], v[48:51]
	v_mfma_f32_16x16x32_bf16 v[52:55], v[222:225], v[92:95], v[52:55]
	v_mfma_f32_16x16x32_bf16 v[40:43], v[226:229], v[112:115], v[40:43]
	v_mfma_f32_16x16x32_bf16 v[44:47], v[226:229], v[92:95], v[44:47]
	v_mfma_f32_16x16x32_bf16 v[36:39], v[230:233], v[112:115], v[36:39]
	v_mfma_f32_16x16x32_bf16 v[32:35], v[230:233], v[92:95], v[32:35]
	v_mfma_f32_16x16x32_bf16 v[24:27], v[234:237], v[112:115], v[24:27]
	ds_read_b128 v[112:115], v165 offset:24576
	ds_read_b128 v[166:169], v165 offset:26624
	ds_read_b128 v[170:173], v165 offset:28672
	ds_read_b128 v[178:181], v165 offset:30720
	v_mfma_f32_16x16x32_bf16 v[28:31], v[234:237], v[92:95], v[28:31]
	s_waitcnt lgkmcnt(0)
	v_mfma_f32_16x16x32_bf16 v[80:83], v[100:103], v[108:111], v[80:83]
	v_mfma_f32_16x16x32_bf16 v[84:87], v[100:103], v[96:99], v[84:87]
	v_mfma_f32_16x16x32_bf16 v[72:75], v[104:107], v[108:111], v[72:75]
	v_mfma_f32_16x16x32_bf16 v[76:79], v[104:107], v[96:99], v[76:79]
	v_mfma_f32_16x16x32_bf16 v[64:67], v[116:119], v[108:111], v[64:67]
	v_mfma_f32_16x16x32_bf16 v[68:71], v[116:119], v[96:99], v[68:71]
	v_mfma_f32_16x16x32_bf16 v[56:59], v[120:123], v[108:111], v[56:59]
	v_mfma_f32_16x16x32_bf16 v[60:63], v[120:123], v[96:99], v[60:63]
	v_mfma_f32_16x16x32_bf16 v[48:51], v[112:115], v[108:111], v[48:51]
	v_mfma_f32_16x16x32_bf16 v[52:55], v[112:115], v[96:99], v[52:55]
	v_mfma_f32_16x16x32_bf16 v[40:43], v[166:169], v[108:111], v[40:43]
	v_mfma_f32_16x16x32_bf16 v[44:47], v[166:169], v[96:99], v[44:47]
	v_mfma_f32_16x16x32_bf16 v[36:39], v[170:173], v[108:111], v[36:39]
	v_mfma_f32_16x16x32_bf16 v[32:35], v[170:173], v[96:99], v[32:35]
	v_mfma_f32_16x16x32_bf16 v[24:27], v[178:181], v[108:111], v[24:27]
	v_mfma_f32_16x16x32_bf16 v[28:31], v[178:181], v[96:99], v[28:31]

; #define LAS __attribute__((address_space(3)))
; DI float shx16(float v) { return __int_as_float(__builtin_amdgcn_ds_swizzle(__float_as_int(v), 0x401F)); }
; DI float shx32(float v, int idx32) { return __int_as_float(__builtin_amdgcn_ds_bpermute(idx32, __float_as_int(v))); }
; DI float fast_exp2(float x) { return __builtin_amdgcn_exp2f(x); }
; DI void attn_item(const Params& p, int layer, int b, int hh, int jq, lchar* sm, float lam, float oml, int tid, int w) {
;     ...
;       for (int m = 0; m < 2; ++m) {
;         float mx = fmaxf(fmaxf(S[m][0][0], S[m][0][1]), fmaxf(S[m][0][2], S[m][0][3]));
; #pragma unroll
;         for (int k16 = 1; k16 < 4; ++k16) mx = fmaxf(fmaxf(mx, fmaxf(S[m][k16][0], S[m][k16][1])), fmaxf(S[m][k16][2], S[m][k16][3]));
;         mx = fmaxf(mx, shx16(mx));
;         mx = fmaxf(mx, shx32(mx, idx32));
;         if (kt == 0 || __builtin_amdgcn_ballot_w64(mx > 8.0f) != 0ull) {
;           const float dlt = kt == 0 ? mx : fmaxf(mx, 0.f);
;           const float alpha = fast_exp2(-dlt);
;           mrun[m] += dlt;
; #pragma unroll
;           for (int dt = 0; dt < 8; ++dt) { O[m][dt][0] *= alpha; O[m][dt][1] *= alpha; O[m][dt][2] *= alpha; O[m][dt][3] *= alpha; }
;           Osum[m][0] *= alpha; Osum[m][1] *= alpha; Osum[m][2] *= alpha; Osum[m][3] *= alpha;
; #pragma unroll
;           for (int k16 = 0; k16 < 4; ++k16)
; #pragma unroll
;             for (int r = 0; r < 4; ++r) S[m][k16][r] -= dlt;
;         }
;     ...
;         bf16x8 vf[8];
; #pragma unroll
;         for (int dt = 0; dt < 8; ++dt) vf[dt] = *(const LAS bf16x8*)(vb + dt * 2048 + voff[kk]);
.LBB0_174:
	v_add_u32_e32 v238, s73, v153
	ds_read_b128 v[206:209], v238 offset:16384
	ds_read_b128 v[210:213], v238 offset:18432
	ds_read_b128 v[214:217], v238 offset:20480
	ds_read_b128 v[218:221], v238 offset:22528
	ds_read_b128 v[222:225], v238 offset:24576
	ds_read_b128 v[226:229], v238 offset:26624
	ds_read_b128 v[230:233], v238 offset:28672
	ds_read_b128 v[234:237], v238 offset:30720
	v_exp_f32_e32 v110, v110
	v_exp_f32_e32 v111, v111
	v_exp_f32_e32 v116, v116
	v_exp_f32_e32 v117, v117
	v_exp_f32_e32 v118, v118
	v_exp_f32_e32 v119, v119
	v_exp_f32_e32 v166, v113
	v_cvt_pk_bf16_f32 v113, v110, v111
	v_cvt_pk_bf16_f32 v110, v116, v117
	v_max3_f32 v116, v92, v93, v94
	v_max3_f32 v117, v95, v96, v97
	v_cvt_pk_bf16_f32 v111, v118, v119
	v_max3_f32 v118, v98, v99, v100
	v_max3_f32 v119, v101, v102, v103
	v_max3_f32 v116, v116, v104, v105
	v_max3_f32 v117, v117, v106, v107
	v_max3_f32 v116, v116, v117, v118
	v_max_f32_e32 v116, v116, v119
	v_mov_b32_e32 v117, v116
	v_exp_f32_e32 v108, v108
	v_exp_f32_e32 v109, v109
	v_permlane16_swap_b32_e32 v116, v117
	v_exp_f32_e32 v165, v112
	v_max_f32_e32 v116, v116, v117
	v_mov_b32_e32 v117, v116
	v_exp_f32_e32 v167, v114
	v_exp_f32_e32 v115, v115
	v_permlane32_swap_b32_e32 v116, v117
	v_exp_f32_e32 v120, v120
	v_exp_f32_e32 v121, v121
	v_exp_f32_e32 v122, v122
	v_exp_f32_e32 v123, v123
	v_cvt_pk_bf16_f32 v112, v108, v109
	v_cvt_pk_bf16_f32 v114, v165, v166
	v_cvt_pk_bf16_f32 v115, v167, v115
	v_max_f32_e32 v116, v116, v117
	v_cmp_lt_f32_e32 vcc, s22, v116
	v_mfma_f32_16x16x32_bf16 v[20:23], v[0:3], v[112:115], v[20:23]
	v_cvt_pk_bf16_f32 v108, v120, v121
	v_cvt_pk_bf16_f32 v109, v122, v123
	s_nop 1
	v_mfma_f32_16x16x32_bf16 v[20:23], v[0:3], v[108:111], v[20:23]
	s_cbranch_vccz .LBB0_167
	v_max_f32_e32 v116, 0, v116
	v_exp_f32_e64 v118, -v116
	v_add_f32_e32 v140, v140, v116
	v_pk_add_f32 v[96:97], v[96:97], v[116:117] op_sel_hi:[1,0] neg_lo:[0,1] neg_hi:[0,1]
	v_pk_add_f32 v[98:99], v[98:99], v[116:117] op_sel_hi:[1,0] neg_lo:[0,1] neg_hi:[0,1]
	v_pk_mul_f32 v[86:87], v[86:87], v[118:119] op_sel_hi:[1,0]
	v_pk_mul_f32 v[84:85], v[84:85], v[118:119] op_sel_hi:[1,0]
	v_pk_mul_f32 v[78:79], v[78:79], v[118:119] op_sel_hi:[1,0]
	v_pk_mul_f32 v[76:77], v[76:77], v[118:119] op_sel_hi:[1,0]
	v_pk_mul_f32 v[70:71], v[70:71], v[118:119] op_sel_hi:[1,0]
	v_pk_mul_f32 v[68:69], v[68:69], v[118:119] op_sel_hi:[1,0]
	v_pk_mul_f32 v[62:63], v[62:63], v[118:119] op_sel_hi:[1,0]
	v_pk_mul_f32 v[60:61], v[60:61], v[118:119] op_sel_hi:[1,0]
	v_pk_mul_f32 v[54:55], v[54:55], v[118:119] op_sel_hi:[1,0]
	v_pk_mul_f32 v[52:53], v[52:53], v[118:119] op_sel_hi:[1,0]
	v_pk_mul_f32 v[46:47], v[46:47], v[118:119] op_sel_hi:[1,0]
	v_pk_mul_f32 v[44:45], v[44:45], v[118:119] op_sel_hi:[1,0]
	v_pk_mul_f32 v[34:35], v[34:35], v[118:119] op_sel_hi:[1,0]
	v_pk_mul_f32 v[32:33], v[32:33], v[118:119] op_sel_hi:[1,0]
	v_pk_mul_f32 v[30:31], v[30:31], v[118:119] op_sel_hi:[1,0]
	v_pk_mul_f32 v[28:29], v[28:29], v[118:119] op_sel_hi:[1,0]
	v_pk_mul_f32 v[90:91], v[90:91], v[118:119] op_sel_hi:[1,0]
	v_pk_mul_f32 v[88:89], v[88:89], v[118:119] op_sel_hi:[1,0]
	v_pk_add_f32 v[92:93], v[92:93], v[116:117] op_sel_hi:[1,0] neg_lo:[0,1] neg_hi:[0,1]
	v_pk_add_f32 v[94:95], v[94:95], v[116:117] op_sel_hi:[1,0] neg_lo:[0,1] neg_hi:[0,1]
	v_pk_add_f32 v[100:101], v[100:101], v[116:117] op_sel_hi:[1,0] neg_lo:[0,1] neg_hi:[0,1]
	v_pk_add_f32 v[102:103], v[102:103], v[116:117] op_sel_hi:[1,0] neg_lo:[0,1] neg_hi:[0,1]
	v_pk_add_f32 v[104:105], v[104:105], v[116:117] op_sel_hi:[1,0] neg_lo:[0,1] neg_hi:[0,1]
	v_pk_add_f32 v[106:107], v[106:107], v[116:117] op_sel_hi:[1,0] neg_lo:[0,1] neg_hi:[0,1]
	s_branch .LBB0_167
